# FoX QK^T: K-fragment LDS reads issued 13 deep with counted lgkmcnt waits, decay-bias reads overlapped with the last MFMAs
# speedup vs baseline: 1.0042x; 1.0042x over previous
; #define LAS __attribute__((address_space(3)))
; #define SBAR() __builtin_amdgcn_sched_barrier(0)
; template <int TYPE>
; __device__ __forceinline__ void attn_item(const Params& p, int layer, int head, int qb, int mode, LAS unsigned char* lds) {
;     ...
;         if (kbase <= w_last) {
;             f32x16 p0 = (f32x16){}, p1 = (f32x16){};
;             const LAS unsigned char* kt = K_lds + bf * SHM_K;
; #pragma unroll
;             for (int d0 = 0; d0 < NQ; ++d0) {
;                 const LAS unsigned char* a = d0 < 8 ? kt + kb[d0 & 3] + (d0 >> 2) * 128 : kt + kbr[d0 & 3];
;                 const bf16x8 b0 = *(const LAS bf16x8*)a, b1 = *(const LAS bf16x8*)(a + (d0 < 8 ? 32 * 256 : 32 * 128));
;                 p0 = __builtin_amdgcn_mfma_f32_32x32x16_bf16(b0, qr[d0], p0, 0, 0, 0);
;                 p1 = __builtin_amdgcn_mfma_f32_32x32x16_bf16(b1, qr[d0], p1, 0, 0, 0);
;                 if ((d0 & 3) == 3) SBAR();
;             }
;             if (TYPE == 1) {
;                 const LAS float* bb = B_lds + bf * 64 + 4 * hi;
; #pragma unroll
;                 for (int q4 = 0; q4 < 4; ++q4) {
;                     const f32x4 b0 = *(const LAS f32x4*)(bb + 8 * q4), b1 = *(const LAS f32x4*)(bb + 32 + 8 * q4);
; #pragma unroll
;                     for (int j = 0; j < 4; ++j) { p0[q4 * 4 + j] += b0[j]; p1[q4 * 4 + j] += b1[j]; }
;                 }
;             }
.LBB0_850:
	s_add_i32 s18, s29, s7
	s_cmp_gt_i32 s18, s31
	s_cbranch_scc1 .LBB0_862
	s_lshl_b32 s4, s11, 14
	s_add_i32 s4, s4, 0
	v_add3_u32 v0, s4, v206, v205
	v_add3_u32 v102, s4, v207, v205
	v_add3_u32 v103, s4, v208, v205
	v_add3_u32 v104, s4, v223, v205
	ds_read_b128 v[66:69], v0 offset:32768
	ds_read_b128 v[70:73], v0 offset:40960
	ds_read_b128 v[162:165], v102 offset:32768
	ds_read_b128 v[166:169], v102 offset:40960
	ds_read_b128 v[170:173], v103 offset:32768
	ds_read_b128 v[174:177], v103 offset:40960
	ds_read_b128 v[228:231], v104 offset:32768
	ds_read_b128 v[232:235], v104 offset:40960
	ds_read_b128 v[236:239], v0 offset:32896
	ds_read_b128 v[240:243], v0 offset:41088
	ds_read_b128 v[244:247], v102 offset:32896
	ds_read_b128 v[194:197], v102 offset:41088
	ds_read_b128 v[248:251], v103 offset:32896
	s_waitcnt lgkmcnt(12)
	v_mfma_f32_32x32x16_bf16 v[82:97], v[66:69], v[130:133], 0
	s_waitcnt lgkmcnt(11)
	v_mfma_f32_32x32x16_bf16 v[66:81], v[70:73], v[130:133], 0
	s_waitcnt lgkmcnt(10)
	v_mfma_f32_32x32x16_bf16 v[82:97], v[162:165], v[134:137], v[82:97]
	ds_read_b128 v[162:165], v103 offset:41088
	s_waitcnt lgkmcnt(10)
	v_mfma_f32_32x32x16_bf16 v[66:81], v[166:169], v[134:137], v[66:81]
	ds_read_b128 v[166:169], v104 offset:32896
	s_waitcnt lgkmcnt(10)
	v_mfma_f32_32x32x16_bf16 v[82:97], v[170:173], v[138:141], v[82:97]
	ds_read_b128 v[170:173], v104 offset:41088
	s_waitcnt lgkmcnt(10)
	v_mfma_f32_32x32x16_bf16 v[66:81], v[174:177], v[138:141], v[66:81]
	s_waitcnt lgkmcnt(9)
	v_mfma_f32_32x32x16_bf16 v[82:97], v[228:231], v[142:145], v[82:97]
	s_waitcnt lgkmcnt(8)
	v_mfma_f32_32x32x16_bf16 v[66:81], v[232:235], v[142:145], v[66:81]
	v_lshl_add_u32 v0, s11, 8, v224
	ds_read_b128 v[98:101], v0
	ds_read_b128 v[102:105], v0 offset:32
	ds_read_b128 v[106:109], v0 offset:64
	ds_read_b128 v[110:113], v0 offset:96
	ds_read_b128 v[114:117], v0 offset:128
	ds_read_b128 v[118:121], v0 offset:160
	ds_read_b128 v[122:125], v0 offset:192
	ds_read_b128 v[126:129], v0 offset:224
	s_waitcnt lgkmcnt(15)
	v_mfma_f32_32x32x16_bf16 v[82:97], v[236:239], v[146:149], v[82:97]
	s_waitcnt lgkmcnt(14)
	v_mfma_f32_32x32x16_bf16 v[66:81], v[240:243], v[146:149], v[66:81]
	s_waitcnt lgkmcnt(13)
	v_mfma_f32_32x32x16_bf16 v[82:97], v[244:247], v[150:153], v[82:97]
	s_waitcnt lgkmcnt(12)
	v_mfma_f32_32x32x16_bf16 v[66:81], v[194:197], v[150:153], v[66:81]
	s_waitcnt lgkmcnt(11)
	v_mfma_f32_32x32x16_bf16 v[82:97], v[248:251], v[154:157], v[82:97]
	s_waitcnt lgkmcnt(10)
	v_mfma_f32_32x32x16_bf16 v[66:81], v[162:165], v[154:157], v[66:81]
	s_waitcnt lgkmcnt(9)
	v_mfma_f32_32x32x16_bf16 v[82:97], v[166:169], v[158:161], v[82:97]
	s_waitcnt lgkmcnt(8)
	v_mfma_f32_32x32x16_bf16 v[66:81], v[170:173], v[158:161], v[66:81]
	s_add_i32 s4, s18, 63
	s_nop 7
	s_nop 3
	s_waitcnt lgkmcnt(0)
	v_pk_add_f32 v[96:97], v[96:97], v[112:113]
	v_pk_add_f32 v[92:93], v[92:93], v[108:109]
	v_pk_add_f32 v[88:89], v[88:89], v[104:105]
	v_pk_add_f32 v[84:85], v[84:85], v[100:101]
	v_pk_add_f32 v[82:83], v[82:83], v[98:99]
	v_pk_add_f32 v[94:95], v[94:95], v[110:111]
	v_pk_add_f32 v[90:91], v[90:91], v[106:107]
	v_pk_add_f32 v[86:87], v[86:87], v[102:103]
	v_pk_add_f32 v[80:81], v[80:81], v[128:129]
	v_pk_add_f32 v[76:77], v[76:77], v[124:125]
	v_pk_add_f32 v[98:99], v[72:73], v[120:121]
	v_pk_add_f32 v[100:101], v[68:69], v[116:117]
	v_pk_add_f32 v[72:73], v[66:67], v[114:115]
	v_pk_add_f32 v[66:67], v[78:79], v[126:127]
	v_pk_add_f32 v[68:69], v[74:75], v[122:123]
	s_cmp_le_i32 s4, s13
	v_pk_add_f32 v[70:71], v[70:71], v[118:119]
	s_cbranch_scc1 .LBB0_853
; template <int TYPE>
; __device__ __forceinline__ void attn_item(const Params& p, int layer, int head, int qb, int mode, LAS unsigned char* lds) {
;     ...
;             if (TYPE == 1 && kbase + 63 > w_first) {
;                 const int lim = my_kmax - kbase - 4 * hi; const float NEGI = -__builtin_inff();
; #pragma unroll
;                 for (int r = 0; r < 16; ++r) { const int c = (r & 3) + 8 * (r >> 2); if (c > lim) p0[r] = NEGI; if (c + 32 > lim) p1[r] = NEGI; }
;             }
	v_cmp_gt_i32_e64 s[4:5], 26, v225
	v_cmp_gt_i32_e32 vcc, 27, v225
	v_cmp_gt_i32_e64 s[96:97], 25, v225
	v_cmp_gt_i32_e64 s[94:95], 24, v225
	v_cndmask_b32_e32 v97, v97, v219, vcc
	s_and_b64 vcc, vcc, s[4:5]
	v_cndmask_b32_e32 v96, v96, v219, vcc
	s_and_b64 vcc, vcc, s[96:97]
	v_cmp_gt_i32_e64 s[92:93], 19, v225
	v_cndmask_b32_e32 v95, v95, v219, vcc
	s_and_b64 vcc, vcc, s[94:95]
	s_mov_b32 s20, s90
	v_cmp_gt_i32_e64 s[90:91], 18, v225
	v_cndmask_b32_e32 v94, v94, v219, vcc
	s_and_b64 vcc, vcc, s[92:93]
	v_cmp_gt_i32_e64 s[88:89], 17, v225
	v_cndmask_b32_e32 v93, v93, v219, vcc
	s_and_b64 vcc, vcc, s[90:91]
	v_cmp_gt_i32_e64 s[86:87], 16, v225
	v_cndmask_b32_e32 v92, v92, v219, vcc
	s_and_b64 vcc, vcc, s[88:89]
	v_cmp_gt_i32_e64 s[84:85], 11, v225
	v_cndmask_b32_e32 v91, v91, v219, vcc
	s_and_b64 vcc, vcc, s[86:87]
	v_cmp_gt_i32_e64 s[82:83], 10, v225
	v_cndmask_b32_e32 v90, v90, v219, vcc
	s_and_b64 vcc, vcc, s[84:85]
	s_mov_b32 s19, s80
	v_cmp_gt_i32_e64 s[80:81], 9, v225
	v_cndmask_b32_e32 v89, v89, v219, vcc
	s_and_b64 vcc, vcc, s[82:83]
	v_cmp_gt_i32_e64 s[78:79], 8, v225
	v_cndmask_b32_e32 v88, v88, v219, vcc
	s_and_b64 vcc, vcc, s[80:81]
	v_cmp_gt_i32_e64 s[76:77], 3, v225
	v_cndmask_b32_e32 v87, v87, v219, vcc
	s_and_b64 vcc, vcc, s[78:79]
	v_cmp_gt_i32_e64 s[74:75], 2, v225
	v_cndmask_b32_e32 v86, v86, v219, vcc
	s_and_b64 vcc, vcc, s[76:77]
	v_cmp_gt_i32_e64 s[72:73], 1, v225
	v_cndmask_b32_e32 v85, v85, v219, vcc
	s_and_b64 vcc, vcc, s[74:75]
	v_cmp_gt_i32_e64 s[70:71], 0, v225
	v_cndmask_b32_e32 v84, v84, v219, vcc
	s_and_b64 vcc, vcc, s[72:73]
	v_cndmask_b32_e32 v83, v83, v219, vcc
	s_and_b64 vcc, vcc, s[70:71]
	v_cmp_gt_i32_e64 s[66:67], 58, v225
	v_cndmask_b32_e32 v82, v82, v219, vcc
	v_cmp_gt_i32_e32 vcc, 59, v225
	v_cmp_gt_i32_e64 s[64:65], 57, v225
	v_cmp_gt_i32_e64 s[62:63], 56, v225
	v_cndmask_b32_e32 v81, v81, v219, vcc
	s_and_b64 vcc, vcc, s[66:67]
	v_cndmask_b32_e32 v80, v80, v219, vcc
	s_and_b64 vcc, vcc, s[64:65]
	v_cmp_gt_i32_e64 s[60:61], 51, v225
	v_cndmask_b32_e32 v67, v67, v219, vcc
	s_and_b64 vcc, vcc, s[62:63]
	v_cmp_gt_i32_e64 s[58:59], 50, v225
	v_cndmask_b32_e32 v66, v66, v219, vcc
	s_and_b64 vcc, vcc, s[60:61]
	v_cmp_gt_i32_e64 s[56:57], 49, v225
	v_cndmask_b32_e32 v77, v77, v219, vcc
	s_and_b64 vcc, vcc, s[58:59]
	v_cmp_gt_i32_e64 s[54:55], 48, v225
	v_cndmask_b32_e32 v76, v76, v219, vcc
	s_and_b64 vcc, vcc, s[56:57]
	v_cmp_gt_i32_e64 s[52:53], 43, v225
	v_cndmask_b32_e32 v69, v69, v219, vcc
	s_and_b64 vcc, vcc, s[54:55]
	v_cmp_gt_i32_e64 s[50:51], 42, v225
	v_cndmask_b32_e32 v68, v68, v219, vcc
	s_and_b64 vcc, vcc, s[52:53]
	v_cmp_gt_i32_e64 s[48:49], 41, v225
	v_cndmask_b32_e32 v99, v99, v219, vcc
	s_and_b64 vcc, vcc, s[50:51]
	v_cmp_gt_i32_e64 s[22:23], 40, v225
	v_cndmask_b32_e32 v98, v98, v219, vcc
	s_and_b64 vcc, vcc, s[48:49]
	v_cmp_gt_i32_e64 s[42:43], 35, v225
	v_cndmask_b32_e32 v71, v71, v219, vcc
	s_and_b64 vcc, vcc, s[22:23]
	v_cmp_gt_i32_e64 s[40:41], 34, v225
	v_cndmask_b32_e32 v70, v70, v219, vcc
	s_and_b64 vcc, vcc, s[42:43]
	v_cmp_gt_i32_e64 s[38:39], 33, v225
	v_cndmask_b32_e32 v101, v101, v219, vcc
	s_and_b64 vcc, vcc, s[40:41]
	v_cmp_gt_i32_e64 s[68:69], 32, v225
	v_cndmask_b32_e32 v100, v100, v219, vcc
	s_and_b64 vcc, vcc, s[38:39]
	s_mov_b32 s88, 0xfffe0000
	s_mov_b32 s86, 0xfff58000
	v_cndmask_b32_e32 v73, v73, v219, vcc
	s_and_b64 vcc, vcc, s[68:69]
	s_mov_b32 s90, s20
	s_mov_b32 s89, -1
	s_mov_b32 s87, -1
	s_mov_b64 s[84:85], 0x20000
	s_mov_b64 s[82:83], 0x40000
	s_movk_i32 s81, 0x2a00
	s_mov_b32 s80, s19
	v_cndmask_b32_e32 v72, v72, v219, vcc
